# D attention loop rotated: previous tile's PV(ks2,ks3) runs under the K-fragment LDS read latency
# speedup vs baseline: 1.0341x; 1.0006x over previous
; #define ALAS __attribute__((address_space(3)))
; template <bool SUB> __device__ __forceinline__ void attn_unit_r2(const AU& u, ALAS unsigned char* lds, float mb2) {
;     ...
;     int tid_o = threadIdx.x; asm volatile("" : "+v"(tid_o));
;     const int tid = tid_o, lane = tid & 63, wid = __builtin_amdgcn_readfirstlane(tid >> 6), r = lane & 31, h = lane >> 5;
;     const int hl = wid / u.wph, qs = u.q0 + 64 * (wid % u.wph);
;     bf16x8 qa[4], qb[4];
;     { const bf16_t* qp = u.Q + (size_t)hl * u.qhs + (size_t)(qs + r) * u.qrs + h * 8;
; #pragma unroll
;       for (int d0 = 0; d0 < 4; ++d0) { qa[d0] = *(const bf16x8*)(qp + d0 * 16); qb[d0] = *(const bf16x8*)(qp + (size_t)32 * u.qrs + d0 * 16); } }
;     const int NT = u.nsub >> 6;
;     const int kr0 = tid >> 3, kc0 = tid & 7;
;     const bf16_t* kg0 = u.K + (size_t)kr0 * u.krs + kc0 * 8; const bf16_t* vg = u.V + (size_t)kr0 * u.vrs + kc0 * 8;
;     const int kl0 = kr0 * KP + kc0 * 16, vl = V_OFF + kr0 * VP + kc0 * 16;
;     f32x16 oa0, oa1, ob0, ob1, negm;
; #pragma unroll
;     for (int i = 0; i < 16; ++i) { oa0[i] = 0.f; oa1[i] = 0.f; ob0[i] = 0.f; ob1[i] = 0.f; negm[i] = SUB ? -mb2 : 0.f; }
;     float la = 0.f, lb = 0.f;
;     u32x4 rk = *(const u32x4*)kg0, rv = *(const u32x4*)vg;
;     *(ALAS u32x4*)(lds + kl0) = rk; *(ALAS u32x4*)(lds + vl) = rv;
;     __syncthreads();
.LBB0_169:
	s_and_b64 vcc, exec, s[52:53]
	s_cbranch_vccz .LBB0_117
	s_and_saveexec_b64 s[20:21], s[38:39]
	s_xor_b64 s[52:53], exec, s[20:21]
	s_cbranch_execz .LBB0_178
	v_mov_b32_e32 v22, v171
	v_mov_b64_e32 v[16:17], s[22:23]
	v_readfirstlane_b32 s2, v22
	s_ashr_i32 s2, s2, 6
	s_lshr_b32 s7, s2, 31
	s_add_i32 s7, s2, s7
	s_ashr_i32 s54, s7, 1
	s_and_b32 s7, s7, 0x3fffffe
	v_ashrrev_i32_e32 v23, 3, v22
	s_movk_i32 s30, 0xc00
	v_lshlrev_b32_e32 v18, 4, v22
	v_mov_b64_e32 v[20:21], s[4:5]
	s_sub_i32 s2, s2, s7
	v_mad_i64_i32 v[16:17], s[20:21], v23, s30, v[16:17]
	v_and_b32_e32 v18, 0x70, v18
	v_mad_i64_i32 v[20:21], s[20:21], v23, s30, v[20:21]
	v_mov_b32_e32 v19, v169
	s_lshl_b32 s2, s2, 6
	v_lshl_add_u64 v[20:21], v[20:21], 0, v[18:19]
	v_lshl_add_u64 v[16:17], v[16:17], 0, v[18:19]
	v_and_b32_e32 v19, 31, v22
	s_ashr_i32 s55, s54, 31
	s_add_i32 s2, s2, s79
	global_load_dwordx4 v[128:131], v[20:21], off
	global_load_dwordx4 v[132:135], v[16:17], off
	s_lshl_b64 s[54:55], s[54:55], 7
	v_or_b32_e32 v16, s2, v19
	s_movk_i32 s7, 0x600
	s_add_u32 s54, s48, s54
	v_mul_lo_u32 v16, v16, s7
	v_bfe_u32 v24, v22, 5, 1
	s_addc_u32 s55, s49, s55
	v_ashrrev_i32_e32 v17, 31, v16
	v_lshlrev_b32_e32 v168, 4, v24
	v_lshl_add_u64 v[16:17], v[16:17], 1, s[54:55]
	v_lshl_add_u64 v[16:17], v[16:17], 0, v[168:169]
	s_mov_b32 s7, 0x18000
	v_add_co_u32_e32 v20, vcc, s7, v16
	v_bfe_u32 v25, v22, 2, 2
	s_nop 0
	v_addc_co_u32_e32 v21, vcc, 0, v17, vcc
	global_load_dwordx4 v[136:139], v[16:17], off
	global_load_dwordx4 v[140:143], v[16:17], off offset:32
	global_load_dwordx4 v[144:147], v[16:17], off offset:64
	global_load_dwordx4 v[148:151], v[16:17], off offset:96
	global_load_dwordx4 v[152:155], v[20:21], off
	global_load_dwordx4 v[156:159], v[20:21], off offset:32
	global_load_dwordx4 v[160:163], v[20:21], off offset:64
	global_load_dwordx4 v[164:167], v[20:21], off offset:96
	v_lshlrev_b32_e32 v16, 1, v22
	v_lshlrev_b32_e32 v17, 3, v22
	s_movk_i32 s7, 0x90
	v_mul_u32_u24_e32 v19, 0x90, v19
	v_lshl_or_b32 v21, v24, 2, v25
	v_and_b32_e32 v22, 32, v16
	v_and_b32_e32 v24, 24, v17
	v_mad_i64_i32 v[16:17], s[54:55], v23, s30, 0
	v_mul_lo_u32 v20, v23, s7
	v_add3_u32 v168, 0, v19, v168
	v_mad_u32_u24 v19, v21, s7, 0
	v_or_b32_e32 v16, v16, v18
	v_mov_b32_e32 v48, 0
	v_add3_u32 v220, v18, v20, 0
	v_add3_u32 v221, v19, v22, v24
	v_lshl_add_u64 v[18:19], s[4:5], 0, v[16:17]
	v_lshl_add_u64 v[16:17], s[22:23], 0, v[16:17]
	s_mov_b32 s21, 0
	v_mov_b32_e32 v49, v48
	v_mov_b32_e32 v50, v48
	v_mov_b32_e32 v51, v48
	v_mov_b32_e32 v52, v48
	v_mov_b32_e32 v53, v48
	v_mov_b32_e32 v54, v48
	v_mov_b32_e32 v55, v48
	v_mov_b32_e32 v56, v48
	v_mov_b32_e32 v57, v48
	v_mov_b32_e32 v58, v48
	v_lshl_add_u64 v[174:175], v[18:19], 0, s[12:13]
	v_lshl_add_u64 v[176:177], v[16:17], 0, s[12:13]
	s_lshr_b32 s7, s78, 6
	v_mov_b32_e32 v59, v48
	v_mov_b32_e32 v60, v48
	v_mov_b32_e32 v61, v48
	v_mov_b32_e32 v62, v48
	v_mov_b32_e32 v63, v48
	v_mov_b32_e32 v64, v48
	v_mov_b32_e32 v65, v48
	v_mov_b32_e32 v66, v48
	v_mov_b32_e32 v67, v48
	v_mov_b32_e32 v68, v48
	v_mov_b32_e32 v69, v48
	v_mov_b32_e32 v70, v48
	v_mov_b32_e32 v71, v48
	v_mov_b32_e32 v72, v48
	v_mov_b32_e32 v73, v48
	v_mov_b32_e32 v74, v48
	v_mov_b32_e32 v75, v48
	v_mov_b32_e32 v76, v48
	v_mov_b32_e32 v77, v48
	v_mov_b32_e32 v78, v48
	v_mov_b32_e32 v79, v48
	v_mov_b32_e32 v16, v48
	v_mov_b32_e32 v17, v48
	v_mov_b32_e32 v18, v48
	v_mov_b32_e32 v19, v48
	v_mov_b32_e32 v20, v48
	v_mov_b32_e32 v21, v48
	v_mov_b32_e32 v22, v48
	v_mov_b32_e32 v23, v48
	v_mov_b32_e32 v24, v48
	v_mov_b32_e32 v25, v48
	v_mov_b32_e32 v26, v48
	v_mov_b32_e32 v27, v48
	v_mov_b32_e32 v28, v48
	v_mov_b32_e32 v29, v48
	v_mov_b32_e32 v30, v48
	v_mov_b32_e32 v31, v48
	v_mov_b32_e32 v32, v48
	v_mov_b32_e32 v33, v48
	v_mov_b32_e32 v34, v48
	v_mov_b32_e32 v35, v48
	v_mov_b32_e32 v36, v48
	v_mov_b32_e32 v37, v48
	v_mov_b32_e32 v38, v48
	v_mov_b32_e32 v39, v48
	v_mov_b32_e32 v40, v48
	v_mov_b32_e32 v41, v48
	v_mov_b32_e32 v42, v48
	v_mov_b32_e32 v43, v48
	v_mov_b32_e32 v44, v48
	v_mov_b32_e32 v45, v48
	v_mov_b32_e32 v46, v48
	v_mov_b32_e32 v47, v48
	v_mov_b32_e32 v172, v48
	v_mov_b32_e32 v173, v48
	v_mov_b32_e32 v242, v48
	v_mov_b32_e32 v243, v48
	v_mov_b32_e32 v112, v48
	v_mov_b32_e32 v113, v48
	v_mov_b32_e32 v114, v48
	v_mov_b32_e32 v115, v48
	v_mov_b32_e32 v116, v48
	v_mov_b32_e32 v117, v48
	v_mov_b32_e32 v118, v48
	v_mov_b32_e32 v119, v48
	v_mov_b32_e32 v120, v48
	v_mov_b32_e32 v121, v48
	v_mov_b32_e32 v122, v48
	v_mov_b32_e32 v123, v48
	v_mov_b32_e32 v124, v48
	v_mov_b32_e32 v125, v48
	v_mov_b32_e32 v126, v48
	v_mov_b32_e32 v127, v48
	v_mov_b32_e32 v0, v48
	v_mov_b32_e32 v1, v48
	v_mov_b32_e32 v2, v48
	v_mov_b32_e32 v3, v48
	v_mov_b32_e32 v4, v48
	v_mov_b32_e32 v5, v48
	v_mov_b32_e32 v6, v48
	v_mov_b32_e32 v7, v48
	v_mov_b32_e32 v8, v48
	v_mov_b32_e32 v9, v48
	v_mov_b32_e32 v10, v48
	v_mov_b32_e32 v11, v48
	v_mov_b32_e32 v12, v48
	v_mov_b32_e32 v13, v48
	v_mov_b32_e32 v14, v48
	v_mov_b32_e32 v15, v48
	v_mov_b32_e32 v80, v48
	v_mov_b32_e32 v81, v48
	v_mov_b32_e32 v82, v48
	v_mov_b32_e32 v83, v48
	v_mov_b32_e32 v84, v48
	v_mov_b32_e32 v85, v48
	v_mov_b32_e32 v86, v48
	v_mov_b32_e32 v87, v48
	v_mov_b32_e32 v88, v48
	v_mov_b32_e32 v89, v48
	v_mov_b32_e32 v90, v48
	v_mov_b32_e32 v91, v48
	v_mov_b32_e32 v92, v48
	v_mov_b32_e32 v93, v48
	v_mov_b32_e32 v94, v48
	v_mov_b32_e32 v95, v48
	v_mov_b32_e32 v96, v48
	v_mov_b32_e32 v97, v48
	v_mov_b32_e32 v98, v48
	v_mov_b32_e32 v99, v48
	v_mov_b32_e32 v100, v48
	v_mov_b32_e32 v101, v48
	v_mov_b32_e32 v102, v48
	v_mov_b32_e32 v103, v48
	v_mov_b32_e32 v104, v48
	v_mov_b32_e32 v105, v48
	v_mov_b32_e32 v106, v48
	v_mov_b32_e32 v107, v48
	v_mov_b32_e32 v108, v48
	v_mov_b32_e32 v109, v48
	v_mov_b32_e32 v110, v48
	v_mov_b32_e32 v111, v48
	v_mov_b32_e32 v178, v48
	v_mov_b32_e32 v179, v48
	v_mov_b32_e32 v180, v48
	v_mov_b32_e32 v181, v48
	v_mov_b32_e32 v182, v48
	v_mov_b32_e32 v183, v48
	v_mov_b32_e32 v184, v48
	v_mov_b32_e32 v185, v48
	v_mov_b32_e32 v186, v48
	v_mov_b32_e32 v187, v48
	v_mov_b32_e32 v188, v48
	v_mov_b32_e32 v189, v48
	v_mov_b32_e32 v190, v48
	v_mov_b32_e32 v191, v48
	v_mov_b32_e32 v192, v48
	v_mov_b32_e32 v193, v48
	v_mov_b32_e32 v194, v48
	v_mov_b32_e32 v195, v48
	v_mov_b32_e32 v196, v48
	v_mov_b32_e32 v197, v48
	v_mov_b32_e32 v210, v48
	v_mov_b32_e32 v211, v48
	v_mov_b32_e32 v212, v48
	v_mov_b32_e32 v213, v48
	v_mov_b32_e32 v238, v48
	v_mov_b32_e32 v239, v48
	v_mov_b32_e32 v240, v48
	v_mov_b32_e32 v241, v48
	v_mov_b32_e32 v248, v48
	v_mov_b32_e32 v249, v48
	v_mov_b32_e32 v250, v48
	v_mov_b32_e32 v251, v48
	s_waitcnt vmcnt(9)
	ds_write_b128 v220, v[128:131]
	s_waitcnt vmcnt(0)
	ds_write_b128 v220, v[132:135] offset:18432
	s_waitcnt lgkmcnt(0)
	v_add_u32_e32 v220, 0x2400, v220
	s_movk_i32 s56, 0x2400
	s_barrier
	s_branch .Lr2n_top

; #define ALAS __attribute__((address_space(3)))
; __device__ __forceinline__ s16x4 vtr(const ALAS unsigned char* p) { return __builtin_bit_cast(s16x4, __builtin_amdgcn_ds_read_tr16_b64_v4i16((ALAS s16x4*)p)); }
; #define AMFMA(a, b, c) __builtin_amdgcn_mfma_f32_32x32x16_bf16((a), (b), (c), 0, 0, 0)
; template <bool SUB> __device__ __forceinline__ void attn_unit_r2(const AU& u, ALAS unsigned char* lds, float mb2) {
;     ...
;             f32x16 Sa0 = negm, Sa1 = negm, Sb0 = negm, Sb1 = negm;
; #pragma unroll
;             for (int d0 = 0; d0 < 4; ++d0) {
;                 const bf16x8 k0 = *(const ALAS bf16x8*)(kb + d0 * 32), k1 = *(const ALAS bf16x8*)(kb + 32 * KP + d0 * 32);
;                 Sa0 = AMFMA(k0, qa[d0], Sa0); Sa1 = AMFMA(k1, qa[d0], Sa1); Sb0 = AMFMA(k0, qb[d0], Sb0); Sb1 = AMFMA(k1, qb[d0], Sb1);
;             }
;     ...
;             for (int ks = 0; ks < 4; ++ks) {
;                 const s16x4 lo0 = vtr(vb + ks * 16 * VP), hi0 = vtr(vb + (ks * 16 + 8) * VP), lo1 = vtr(vb + ks * 16 * VP + 64), hi1 = vtr(vb + (ks * 16 + 8) * VP + 64);
;                 const bf16x8 vf0 = __builtin_shufflevector(lo0, hi0, 0, 1, 2, 3, 4, 5, 6, 7), vf1 = __builtin_shufflevector(lo1, hi1, 0, 1, 2, 3, 4, 5, 6, 7);
;                 oa0 = AMFMA(paa[ks], vf0, oa0); oa1 = AMFMA(paa[ks], vf1, oa1); ob0 = AMFMA(pab[ks], vf0, ob0); ob1 = AMFMA(pab[ks], vf1, ob1);
;             }
.Lr2n_noload:
	ds_read_b128 v[222:225], v168 offset:0
	ds_read_b128 v[226:229], v168 offset:32
	ds_read_b128 v[230:233], v168 offset:64
	ds_read_b128 v[234:237], v168 offset:96
	v_mfma_f32_32x32x16_bf16 v[48:63], v[178:181], v[238:241], v[48:63]
	v_add_f32_e32 v172, v96, v172
	v_add_f32_e32 v173, v80, v173
	v_add_f32_e32 v172, v97, v172
	v_add_f32_e32 v173, v81, v173
	v_mfma_f32_32x32x16_bf16 v[64:79], v[178:181], v[248:251], v[64:79]
	v_add_f32_e32 v172, v98, v172
	v_add_f32_e32 v173, v82, v173
	v_add_f32_e32 v172, v99, v172
	v_add_f32_e32 v173, v83, v173
	ds_read_b128 v[178:181], v168 offset:4608
	v_mfma_f32_32x32x16_bf16 v[16:31], v[182:185], v[238:241], v[16:31]
	v_add_f32_e32 v172, v100, v172
	v_add_f32_e32 v173, v84, v173
	v_add_f32_e32 v172, v101, v172
	v_add_f32_e32 v173, v85, v173
	v_mfma_f32_32x32x16_bf16 v[32:47], v[182:185], v[248:251], v[32:47]
	v_add_f32_e32 v172, v102, v172
	v_add_f32_e32 v173, v86, v173
	v_add_f32_e32 v172, v103, v172
	v_add_f32_e32 v173, v87, v173
	ds_read_b128 v[182:185], v168 offset:4640
	v_mfma_f32_32x32x16_bf16 v[48:63], v[186:189], v[194:197], v[48:63]
	v_add_f32_e32 v172, v104, v172
	v_add_f32_e32 v173, v88, v173
	v_add_f32_e32 v172, v105, v172
	v_add_f32_e32 v173, v89, v173
	v_mfma_f32_32x32x16_bf16 v[64:79], v[186:189], v[210:213], v[64:79]
	v_add_f32_e32 v172, v106, v172
	v_add_f32_e32 v173, v90, v173
	v_add_f32_e32 v172, v107, v172
	v_add_f32_e32 v173, v91, v173
	ds_read_b128 v[186:189], v168 offset:4672
	v_mfma_f32_32x32x16_bf16 v[16:31], v[190:193], v[194:197], v[16:31]
	v_add_f32_e32 v172, v108, v172
	v_add_f32_e32 v173, v92, v173
	v_add_f32_e32 v172, v109, v172
	v_add_f32_e32 v173, v93, v173
	v_mfma_f32_32x32x16_bf16 v[32:47], v[190:193], v[210:213], v[32:47]
	v_add_f32_e32 v172, v110, v172
	v_add_f32_e32 v173, v94, v173
	v_add_f32_e32 v172, v111, v172
	v_add_f32_e32 v173, v95, v173
	ds_read_b128 v[190:193], v168 offset:4704
	s_waitcnt lgkmcnt(7)
	v_mfma_f32_32x32x16_bf16 v[96:111], v[222:225], v[136:139], 0
	v_lshl_add_u64 v[174:175], v[174:175], 0, s[12:13]
	v_add_f32_e32 v242, v112, v242
	v_add_f32_e32 v243, v0, v243
	v_add_f32_e32 v242, v113, v242
	v_add_f32_e32 v243, v1, v243
	v_add_f32_e32 v242, v114, v242
	s_waitcnt lgkmcnt(6)
	v_mfma_f32_32x32x16_bf16 v[96:111], v[226:229], v[140:143], v[96:111]
	v_lshl_add_u64 v[176:177], v[176:177], 0, s[12:13]
	v_add_f32_e32 v243, v2, v243
	v_add_f32_e32 v242, v115, v242
	v_add_f32_e32 v243, v3, v243
	v_add_f32_e32 v242, v116, v242
	v_add_f32_e32 v243, v4, v243
	s_waitcnt lgkmcnt(5)
	v_mfma_f32_32x32x16_bf16 v[96:111], v[230:233], v[144:147], v[96:111]
	v_add_f32_e32 v242, v117, v242
	v_add_f32_e32 v243, v5, v243
	v_add_f32_e32 v242, v118, v242
	v_add_f32_e32 v243, v6, v243
	v_add_f32_e32 v242, v119, v242
	v_add_f32_e32 v243, v7, v243
	s_waitcnt lgkmcnt(4)
	v_mfma_f32_32x32x16_bf16 v[96:111], v[234:237], v[148:151], v[96:111]
	v_add_f32_e32 v242, v120, v242
	v_add_f32_e32 v243, v8, v243
	v_add_f32_e32 v242, v121, v242
	v_add_f32_e32 v243, v9, v243
	v_add_f32_e32 v242, v122, v242
	v_add_f32_e32 v243, v10, v243
	v_add_f32_e32 v242, v123, v242
	v_add_f32_e32 v243, v11, v243
	v_mfma_f32_32x32x16_bf16 v[80:95], v[222:225], v[152:155], 0
	v_add_f32_e32 v242, v124, v242
	v_add_f32_e32 v243, v12, v243
	v_add_f32_e32 v242, v125, v242
	v_add_f32_e32 v243, v13, v243
	v_add_f32_e32 v242, v126, v242
	v_add_f32_e32 v243, v14, v243
	v_add_f32_e32 v242, v127, v242
	v_add_f32_e32 v243, v15, v243
	v_mfma_f32_32x32x16_bf16 v[80:95], v[226:229], v[156:159], v[80:95]
	v_exp_f32_e32 v96, v96
	v_exp_f32_e32 v97, v97
	v_exp_f32_e32 v98, v98
	v_exp_f32_e32 v99, v99
	v_mfma_f32_32x32x16_bf16 v[80:95], v[230:233], v[160:163], v[80:95]
	v_exp_f32_e32 v100, v100
	v_exp_f32_e32 v101, v101
	v_exp_f32_e32 v102, v102
	v_exp_f32_e32 v103, v103
	v_mfma_f32_32x32x16_bf16 v[80:95], v[234:237], v[164:167], v[80:95]
	v_exp_f32_e32 v104, v104
	v_exp_f32_e32 v105, v105
	v_exp_f32_e32 v106, v106
	v_exp_f32_e32 v107, v107
	s_waitcnt lgkmcnt(3)
	v_mfma_f32_32x32x16_bf16 v[112:127], v[178:181], v[136:139], 0
	v_exp_f32_e32 v108, v108
	v_exp_f32_e32 v109, v109
	v_exp_f32_e32 v110, v110
	v_exp_f32_e32 v111, v111
	s_waitcnt lgkmcnt(2)
	v_mfma_f32_32x32x16_bf16 v[112:127], v[182:185], v[140:143], v[112:127]
	v_cvt_pk_bf16_f32 v222, v96, v97
	v_cvt_pk_bf16_f32 v223, v98, v99
	v_cvt_pk_bf16_f32 v224, v100, v101
	v_cvt_pk_bf16_f32 v225, v102, v103
	v_exp_f32_e32 v80, v80
	v_exp_f32_e32 v81, v81
	s_waitcnt lgkmcnt(1)
	v_mfma_f32_32x32x16_bf16 v[112:127], v[186:189], v[144:147], v[112:127]
	v_exp_f32_e32 v82, v82
	v_exp_f32_e32 v83, v83
	v_exp_f32_e32 v84, v84
	v_exp_f32_e32 v85, v85
	s_waitcnt lgkmcnt(0)
	v_mfma_f32_32x32x16_bf16 v[112:127], v[190:193], v[148:151], v[112:127]
	v_exp_f32_e32 v86, v86
	v_exp_f32_e32 v87, v87
	v_cvt_pk_bf16_f32 v230, v104, v105
	v_cvt_pk_bf16_f32 v231, v106, v107
	v_cvt_pk_bf16_f32 v232, v108, v109
	v_cvt_pk_bf16_f32 v233, v110, v111
	v_mfma_f32_32x32x16_bf16 v[0:15], v[178:181], v[152:155], 0
	v_exp_f32_e32 v88, v88
	v_exp_f32_e32 v89, v89
	v_exp_f32_e32 v90, v90
	v_exp_f32_e32 v91, v91
	ds_read_b64_tr_b16 v[238:239], v221 offset:18432
	ds_read_b64_tr_b16 v[240:241], v221 offset:19584
	ds_read_b64_tr_b16 v[248:249], v221 offset:18496
	ds_read_b64_tr_b16 v[250:251], v221 offset:19648
	v_mfma_f32_32x32x16_bf16 v[0:15], v[182:185], v[156:159], v[0:15]
	v_exp_f32_e32 v92, v92
	v_exp_f32_e32 v93, v93
	v_exp_f32_e32 v94, v94
	v_exp_f32_e32 v95, v95
	v_mfma_f32_32x32x16_bf16 v[0:15], v[186:189], v[160:163], v[0:15]
	v_cvt_pk_bf16_f32 v226, v80, v81
	v_cvt_pk_bf16_f32 v227, v82, v83
	v_cvt_pk_bf16_f32 v228, v84, v85
	v_cvt_pk_bf16_f32 v229, v86, v87
	v_exp_f32_e32 v112, v112
	v_exp_f32_e32 v113, v113
	v_mfma_f32_32x32x16_bf16 v[0:15], v[190:193], v[164:167], v[0:15]
	v_exp_f32_e32 v114, v114
	v_exp_f32_e32 v115, v115
	v_exp_f32_e32 v116, v116
	v_exp_f32_e32 v117, v117
	ds_read_b64_tr_b16 v[194:195], v221 offset:20736
	ds_read_b64_tr_b16 v[196:197], v221 offset:21888
	ds_read_b64_tr_b16 v[210:211], v221 offset:20800
	ds_read_b64_tr_b16 v[212:213], v221 offset:21952
	s_waitcnt lgkmcnt(6)
; #define ALAS __attribute__((address_space(3)))
; __device__ __forceinline__ s16x4 vtr(const ALAS unsigned char* p) { return __builtin_bit_cast(s16x4, __builtin_amdgcn_ds_read_tr16_b64_v4i16((ALAS s16x4*)p)); }
; #define AMFMA(a, b, c) __builtin_amdgcn_mfma_f32_32x32x16_bf16((a), (b), (c), 0, 0, 0)
; template <bool SUB> __device__ __forceinline__ void attn_unit_r2(const AU& u, ALAS unsigned char* lds, float mb2) {
;     ...
;             for (int ks = 0; ks < 4; ++ks) {
;                 const s16x4 lo0 = vtr(vb + ks * 16 * VP), hi0 = vtr(vb + (ks * 16 + 8) * VP), lo1 = vtr(vb + ks * 16 * VP + 64), hi1 = vtr(vb + (ks * 16 + 8) * VP + 64);
;                 const bf16x8 vf0 = __builtin_shufflevector(lo0, hi0, 0, 1, 2, 3, 4, 5, 6, 7), vf1 = __builtin_shufflevector(lo1, hi1, 0, 1, 2, 3, 4, 5, 6, 7);
;                 oa0 = AMFMA(paa[ks], vf0, oa0); oa1 = AMFMA(paa[ks], vf1, oa1); ob0 = AMFMA(pab[ks], vf0, ob0); ob1 = AMFMA(pab[ks], vf1, ob1);
;             }
;         }
;         if (t + 1 < NT) { *(ALAS u32x4*)(lds + (cur ^ 1) * KBUF + kl0) = rk; *(ALAS u32x4*)(lds + (cur ^ 1) * VBUF + vl) = rv; }
;         __syncthreads();
;     }
;     la += __shfl_xor(la, 32); lb += __shfl_xor(lb, 32);
	v_mfma_f32_32x32x16_bf16 v[48:63], v[222:225], v[238:241], v[48:63]
	v_exp_f32_e32 v118, v118
	v_exp_f32_e32 v119, v119
	v_exp_f32_e32 v120, v120
	v_exp_f32_e32 v121, v121
	s_waitcnt lgkmcnt(4)
	v_mfma_f32_32x32x16_bf16 v[64:79], v[222:225], v[248:251], v[64:79]
	v_cvt_pk_bf16_f32 v234, v88, v89
	v_cvt_pk_bf16_f32 v235, v90, v91
	v_cvt_pk_bf16_f32 v236, v92, v93
	v_cvt_pk_bf16_f32 v237, v94, v95
	v_exp_f32_e32 v122, v122
	v_exp_f32_e32 v123, v123
	v_mfma_f32_32x32x16_bf16 v[16:31], v[226:229], v[238:241], v[16:31]
	v_exp_f32_e32 v124, v124
	v_exp_f32_e32 v125, v125
	v_exp_f32_e32 v126, v126
	v_exp_f32_e32 v127, v127
	v_mfma_f32_32x32x16_bf16 v[32:47], v[226:229], v[248:251], v[32:47]
	ds_read_b64_tr_b16 v[238:239], v221 offset:23040
	ds_read_b64_tr_b16 v[240:241], v221 offset:24192
	ds_read_b64_tr_b16 v[248:249], v221 offset:23104
	ds_read_b64_tr_b16 v[250:251], v221 offset:24256
	v_exp_f32_e32 v0, v0
	v_exp_f32_e32 v1, v1
	v_exp_f32_e32 v2, v2
	v_exp_f32_e32 v3, v3
	s_waitcnt lgkmcnt(6)
	v_mfma_f32_32x32x16_bf16 v[48:63], v[230:233], v[194:197], v[48:63]
	v_exp_f32_e32 v4, v4
	v_exp_f32_e32 v5, v5
	v_exp_f32_e32 v6, v6
	v_exp_f32_e32 v7, v7
	s_waitcnt lgkmcnt(4)
	v_mfma_f32_32x32x16_bf16 v[64:79], v[230:233], v[210:213], v[64:79]
	v_cvt_pk_bf16_f32 v178, v112, v113
	v_cvt_pk_bf16_f32 v179, v114, v115
	v_cvt_pk_bf16_f32 v180, v116, v117
	v_cvt_pk_bf16_f32 v181, v118, v119
	v_exp_f32_e32 v8, v8
	v_exp_f32_e32 v9, v9
	v_mfma_f32_32x32x16_bf16 v[16:31], v[234:237], v[194:197], v[16:31]
	v_exp_f32_e32 v10, v10
	v_exp_f32_e32 v11, v11
	v_exp_f32_e32 v12, v12
	v_exp_f32_e32 v13, v13
	s_andn2_b64 vcc, exec, s[54:55]
	v_mfma_f32_32x32x16_bf16 v[32:47], v[234:237], v[210:213], v[32:47]
	ds_read_b64_tr_b16 v[194:195], v221 offset:25344
	ds_read_b64_tr_b16 v[196:197], v221 offset:26496
	ds_read_b64_tr_b16 v[210:211], v221 offset:25408
	ds_read_b64_tr_b16 v[212:213], v221 offset:26560
	v_exp_f32_e32 v14, v14
	v_exp_f32_e32 v15, v15
	v_cvt_pk_bf16_f32 v182, v0, v1
	v_cvt_pk_bf16_f32 v183, v2, v3
	v_cvt_pk_bf16_f32 v184, v4, v5
	v_cvt_pk_bf16_f32 v185, v6, v7
	v_cvt_pk_bf16_f32 v186, v120, v121
	v_cvt_pk_bf16_f32 v187, v122, v123
	v_cvt_pk_bf16_f32 v188, v124, v125
	v_cvt_pk_bf16_f32 v189, v126, v127
	v_cvt_pk_bf16_f32 v190, v8, v9
	v_cvt_pk_bf16_f32 v191, v10, v11
	v_cvt_pk_bf16_f32 v192, v12, v13
	v_cvt_pk_bf16_f32 v193, v14, v15
	s_cbranch_vccnz .Lr2n_nowrite
	s_waitcnt vmcnt(0)
	ds_write_b128 v220, v[128:131]
	ds_write_b128 v220, v[132:135] offset:18432
.Lr2n_nowrite:
	v_add_u32_e32 v168, s56, v168
	v_add_u32_e32 v221, s56, v221
	v_subrev_u32_e32 v220, s56, v220
	s_sub_i32 s56, 0, s56
	s_cmp_lg_u32 s7, s20
	s_mov_b32 s21, s20
	s_waitcnt lgkmcnt(0)
	s_barrier
	s_cbranch_scc1 .Lr2n_top
	v_mfma_f32_32x32x16_bf16 v[48:63], v[178:181], v[238:241], v[48:63]
	v_add_f32_e32 v172, v96, v172
	v_add_f32_e32 v173, v80, v173
	v_add_f32_e32 v172, v97, v172
	v_add_f32_e32 v173, v81, v173
	v_mfma_f32_32x32x16_bf16 v[64:79], v[178:181], v[248:251], v[64:79]
	v_add_f32_e32 v172, v98, v172
	v_add_f32_e32 v173, v82, v173
	v_add_f32_e32 v172, v99, v172
	v_add_f32_e32 v173, v83, v173
	v_mfma_f32_32x32x16_bf16 v[16:31], v[182:185], v[238:241], v[16:31]
	v_add_f32_e32 v172, v100, v172
	v_add_f32_e32 v173, v84, v173
	v_add_f32_e32 v172, v101, v172
	v_add_f32_e32 v173, v85, v173
	v_mfma_f32_32x32x16_bf16 v[32:47], v[182:185], v[248:251], v[32:47]
	v_add_f32_e32 v172, v102, v172
	v_add_f32_e32 v173, v86, v173
	v_add_f32_e32 v172, v103, v172
	v_add_f32_e32 v173, v87, v173
	v_mfma_f32_32x32x16_bf16 v[48:63], v[186:189], v[194:197], v[48:63]
	v_add_f32_e32 v172, v104, v172
	v_add_f32_e32 v173, v88, v173
	v_add_f32_e32 v172, v105, v172
	v_add_f32_e32 v173, v89, v173
	v_mfma_f32_32x32x16_bf16 v[64:79], v[186:189], v[210:213], v[64:79]
	v_add_f32_e32 v172, v106, v172
	v_add_f32_e32 v173, v90, v173
	v_add_f32_e32 v172, v107, v172
	v_add_f32_e32 v173, v91, v173
	v_mfma_f32_32x32x16_bf16 v[16:31], v[190:193], v[194:197], v[16:31]
	v_add_f32_e32 v172, v108, v172
	v_add_f32_e32 v173, v92, v173
	v_add_f32_e32 v172, v109, v172
	v_add_f32_e32 v173, v93, v173
	v_mfma_f32_32x32x16_bf16 v[32:47], v[190:193], v[210:213], v[32:47]
	v_add_f32_e32 v172, v110, v172
	v_add_f32_e32 v173, v94, v173
	v_add_f32_e32 v172, v111, v172
	v_add_f32_e32 v173, v95, v173
	v_add_f32_e32 v242, v112, v242
	v_add_f32_e32 v243, v0, v243
	v_add_f32_e32 v242, v113, v242
	v_add_f32_e32 v243, v1, v243
	v_add_f32_e32 v242, v114, v242
	v_add_f32_e32 v243, v2, v243
	v_add_f32_e32 v242, v115, v242
	v_add_f32_e32 v243, v3, v243
	v_add_f32_e32 v242, v116, v242
	v_add_f32_e32 v243, v4, v243
	v_add_f32_e32 v242, v117, v242
	v_add_f32_e32 v243, v5, v243
	v_add_f32_e32 v242, v118, v242
	v_add_f32_e32 v243, v6, v243
	v_add_f32_e32 v242, v119, v242
	v_add_f32_e32 v243, v7, v243
	v_add_f32_e32 v242, v120, v242
	v_add_f32_e32 v243, v8, v243
	v_add_f32_e32 v242, v121, v242
	v_add_f32_e32 v243, v9, v243
	v_add_f32_e32 v242, v122, v242
	v_add_f32_e32 v243, v10, v243
	v_add_f32_e32 v242, v123, v242
	v_add_f32_e32 v243, v11, v243
	v_add_f32_e32 v242, v124, v242
	v_add_f32_e32 v243, v12, v243
	v_add_f32_e32 v242, v125, v242
	v_add_f32_e32 v243, v13, v243
	v_add_f32_e32 v242, v126, v242
	v_add_f32_e32 v243, v14, v243
	v_add_f32_e32 v242, v127, v242
	v_add_f32_e32 v243, v15, v243
	v_add_f32_e32 v172, v172, v242
	v_add_f32_e32 v173, v173, v243
	v_xor_b32_e32 v0, 0x80000000, v219
	v_mov_b32_e32 v1, v0
	v_mov_b32_e32 v2, v0
	v_mov_b32_e32 v3, v0
	v_mov_b32_e32 v4, v0
	v_mov_b32_e32 v5, v0
	v_mov_b32_e32 v6, v0
	v_mov_b32_e32 v7, v0
	v_mov_b32_e32 v8, v0
	v_mov_b32_e32 v9, v0
	v_mov_b32_e32 v10, v0
	v_mov_b32_e32 v11, v0
	v_mov_b32_e32 v12, v0
	v_mov_b32_e32 v13, v0
	v_mov_b32_e32 v14, v0
	v_mov_b32_e32 v15, v0
